# GEMM tile epilogue runs at wave priority 1 (above the co-resident workgroup's LDS-write phase, below its MFMA phase)
# speedup vs baseline: 1.0098x; 1.0098x over previous
; #define GLOADS(K0) { _Pragma("unroll") for (int i = 0; i < 8; ++i) ra[i] = *(const u32x4*)(Ap + (size_t)(32 * i) * lda + (K0)); \
;                      _Pragma("unroll") for (int i = 0; i < 4; ++i) rb[i] = *(const u32x4*)(Bp + (size_t)(32 * i) * ldb + (K0)); }
; DI void gemm_phase_(const GemmDesc& d, unsigned char* smem, const XMap& xm) {
;     ...
;   for (int tile = tstart; tile < tend; tile += tstep) {
;     DECODE(tile, z, mt, nt);
;     Ap = A + z * sA + (size_t)(mt * 256 + lrow) * lda + lcc;
;     Bp = Bt + z * sB + (size_t)(nt * 128 + lrow) * ldb + lcc;
;     GLOADS(0);
;     f32x16 acc[4][2];
; #pragma unroll
;     for (int i = 0; i < 4; ++i)
; #pragma unroll
;       for (int j = 0; j < 2; ++j)
; #pragma unroll
;         for (int r = 0; r < 16; ++r) acc[i][j][r] = 0.f;
.LBB0_613:
	s_ashr_i32 s15, s14, 31
	v_readlane_b32 s18, v249, 19
	v_readlane_b32 s19, v249, 20
	s_mul_hi_u32 s3, s18, s14
	s_mul_i32 s10, s18, s15
	s_add_i32 s3, s3, s10
	s_mul_i32 s10, s19, s14
	s_add_i32 s11, s3, s10
	s_mul_i32 s10, s18, s14
	s_lshl_b64 s[10:11], s[10:11], 1
	v_readlane_b32 s18, v249, 26
	v_readlane_b32 s19, v249, 27
	s_add_u32 s10, s18, s10
	s_addc_u32 s11, s19, s11
	s_lshl_b32 s59, s67, 8
	s_waitcnt lgkmcnt(0)
	v_add_u32_e32 v0, s59, v213
	v_mad_i64_i32 v[0:1], s[18:19], v0, s48, 0
	v_lshl_add_u64 v[0:1], v[0:1], 1, s[10:11]
	s_mul_hi_u32 s3, s4, s14
	s_mul_i32 s10, s4, s15
	s_add_i32 s3, s3, s10
	s_mul_i32 s10, s5, s14
	s_add_i32 s11, s3, s10
	s_mul_i32 s10, s4, s14
	s_lshl_b64 s[10:11], s[10:11], 1
	s_add_u32 s10, s50, s10
	v_mov_b32_e32 v197, v177
	s_addc_u32 s11, s51, s11
	s_lshl_b32 s58, s2, 7
	v_readlane_b32 s2, v252, 60
	v_lshl_add_u64 v[198:199], v[0:1], 0, v[196:197]
	v_add_u32_e32 v0, s58, v213
	v_readlane_b32 s3, v252, 61
	v_mad_i64_i32 v[0:1], s[2:3], v0, s2, 0
	v_lshl_add_u64 v[0:1], v[0:1], 1, s[10:11]
	v_readlane_b32 s2, v249, 44
	v_lshl_add_u64 v[200:201], v[0:1], 0, v[196:197]
	v_readlane_b32 s3, v249, 45
	s_mov_b32 s28, 64
	s_nop 0
	v_lshl_add_u64 v[0:1], s[2:3], 1, v[200:201]
	v_readlane_b32 s2, v248, 14
	v_readlane_b32 s3, v248, 15
	s_nop 1
	v_lshl_add_u64 v[2:3], v[0:1], 0, s[2:3]
	v_lshl_add_u64 v[4:5], v[2:3], 0, s[2:3]
	v_readlane_b32 s2, v249, 42
	v_readlane_b32 s3, v249, 43
	global_load_dwordx4 v[152:155], v[2:3], off
	global_load_dwordx4 v[128:131], v[4:5], off
	global_load_dwordx4 v[172:175], v[0:1], off
	global_load_dwordx4 v[132:135], v[200:201], off
	v_lshl_add_u64 v[0:1], s[2:3], 1, v[198:199]
	v_lshl_add_u64 v[2:3], v[0:1], 0, s[6:7]
	global_load_dwordx4 v[148:151], v[0:1], off
	global_load_dwordx4 v[136:139], v[2:3], off
	v_lshl_add_u64 v[0:1], v[2:3], 0, s[6:7]
	v_lshl_add_u64 v[2:3], v[0:1], 0, s[6:7]
	global_load_dwordx4 v[156:159], v[0:1], off
	global_load_dwordx4 v[160:163], v[2:3], off
	v_lshl_add_u64 v[0:1], v[2:3], 0, s[6:7]
	v_lshl_add_u64 v[2:3], v[0:1], 0, s[6:7]
	global_load_dwordx4 v[164:167], v[0:1], off
	global_load_dwordx4 v[168:171], v[2:3], off
	v_lshl_add_u64 v[0:1], v[2:3], 0, s[6:7]
	global_load_dwordx4 v[140:143], v[0:1], off
	global_load_dwordx4 v[144:147], v[198:199], off
	v_mov_b32_e32 v0, 0
	s_mov_b32 s2, 0
	v_mov_b32_e32 v1, v0
	v_mov_b32_e32 v2, v0
	v_mov_b32_e32 v3, v0
	v_mov_b32_e32 v4, v0
	v_mov_b32_e32 v5, v0
	v_mov_b32_e32 v6, v0
	v_mov_b32_e32 v7, v0
	v_mov_b32_e32 v8, v0
	v_mov_b32_e32 v9, v0
	v_mov_b32_e32 v10, v0
	v_mov_b32_e32 v11, v0
	v_mov_b32_e32 v12, v0
	v_mov_b32_e32 v13, v0
	v_mov_b32_e32 v14, v0
	v_mov_b32_e32 v15, v0
	v_mov_b32_e32 v32, v0
	v_mov_b32_e32 v33, v0
	v_mov_b32_e32 v34, v0
	v_mov_b32_e32 v35, v0
	v_mov_b32_e32 v36, v0
	v_mov_b32_e32 v37, v0
	v_mov_b32_e32 v38, v0
	v_mov_b32_e32 v39, v0
	v_mov_b32_e32 v40, v0
	v_mov_b32_e32 v41, v0
	v_mov_b32_e32 v42, v0
	v_mov_b32_e32 v43, v0
	v_mov_b32_e32 v44, v0
	v_mov_b32_e32 v45, v0
	v_mov_b32_e32 v46, v0
	v_mov_b32_e32 v47, v0
	v_mov_b32_e32 v16, v0
	v_mov_b32_e32 v17, v0
	v_mov_b32_e32 v18, v0
	v_mov_b32_e32 v19, v0
	v_mov_b32_e32 v20, v0
	v_mov_b32_e32 v21, v0
	v_mov_b32_e32 v22, v0
	v_mov_b32_e32 v23, v0
	v_mov_b32_e32 v24, v0
	v_mov_b32_e32 v25, v0
	v_mov_b32_e32 v26, v0
	v_mov_b32_e32 v27, v0
	v_mov_b32_e32 v28, v0
	v_mov_b32_e32 v29, v0
	v_mov_b32_e32 v30, v0
	v_mov_b32_e32 v31, v0
	v_mov_b32_e32 v48, v0
	v_mov_b32_e32 v49, v0
	v_mov_b32_e32 v50, v0
	v_mov_b32_e32 v51, v0
	v_mov_b32_e32 v52, v0
	v_mov_b32_e32 v53, v0
	v_mov_b32_e32 v54, v0
	v_mov_b32_e32 v55, v0
	v_mov_b32_e32 v56, v0
	v_mov_b32_e32 v57, v0
	v_mov_b32_e32 v58, v0
	v_mov_b32_e32 v59, v0
	v_mov_b32_e32 v60, v0
	v_mov_b32_e32 v61, v0
	v_mov_b32_e32 v62, v0
	v_mov_b32_e32 v63, v0
	v_mov_b32_e32 v64, v0
	v_mov_b32_e32 v65, v0
	v_mov_b32_e32 v66, v0
	v_mov_b32_e32 v67, v0
	v_mov_b32_e32 v68, v0
	v_mov_b32_e32 v69, v0
	v_mov_b32_e32 v70, v0
	v_mov_b32_e32 v71, v0
	v_mov_b32_e32 v72, v0
	v_mov_b32_e32 v73, v0
	v_mov_b32_e32 v74, v0
	v_mov_b32_e32 v75, v0
	v_mov_b32_e32 v76, v0
	v_mov_b32_e32 v77, v0
	v_mov_b32_e32 v78, v0
	v_mov_b32_e32 v79, v0
	v_mov_b32_e32 v96, v0
	v_mov_b32_e32 v97, v0
	v_mov_b32_e32 v98, v0
	v_mov_b32_e32 v99, v0
	v_mov_b32_e32 v100, v0
	v_mov_b32_e32 v101, v0
	v_mov_b32_e32 v102, v0
	v_mov_b32_e32 v103, v0
	v_mov_b32_e32 v104, v0
	v_mov_b32_e32 v105, v0
	v_mov_b32_e32 v106, v0
	v_mov_b32_e32 v107, v0
	v_mov_b32_e32 v108, v0
	v_mov_b32_e32 v109, v0
	v_mov_b32_e32 v110, v0
	v_mov_b32_e32 v111, v0
	v_mov_b32_e32 v80, v0
	v_mov_b32_e32 v81, v0
	v_mov_b32_e32 v82, v0
	v_mov_b32_e32 v83, v0
	v_mov_b32_e32 v84, v0
	v_mov_b32_e32 v85, v0
	v_mov_b32_e32 v86, v0
	v_mov_b32_e32 v87, v0
	v_mov_b32_e32 v88, v0
	v_mov_b32_e32 v89, v0
	v_mov_b32_e32 v90, v0
	v_mov_b32_e32 v91, v0
	v_mov_b32_e32 v92, v0
	v_mov_b32_e32 v93, v0
	v_mov_b32_e32 v94, v0
	v_mov_b32_e32 v95, v0
	v_mov_b32_e32 v112, v0
	v_mov_b32_e32 v113, v0
	v_mov_b32_e32 v114, v0
	v_mov_b32_e32 v115, v0
	v_mov_b32_e32 v116, v0
	v_mov_b32_e32 v117, v0
	v_mov_b32_e32 v118, v0
	v_mov_b32_e32 v119, v0
	v_mov_b32_e32 v120, v0
	v_mov_b32_e32 v121, v0
	v_mov_b32_e32 v122, v0
	v_mov_b32_e32 v123, v0
	v_mov_b32_e32 v124, v0
	v_mov_b32_e32 v125, v0
	v_mov_b32_e32 v126, v0
	v_mov_b32_e32 v127, v0
	v_lshlrev_b32_e32 v234, 2, v215
	v_add_u32_e32 v234, 0xde20, v234
	ds_write_b128 v234, v[202:205]
	ds_write_b128 v234, v[208:211] offset:4096
	ds_write_b128 v234, v[180:183] offset:8192
	ds_write_b128 v234, v[184:187] offset:12288
	ds_write_b128 v234, v[192:195] offset:16384
	s_waitcnt vmcnt(0)
	s_setprio 0

; DI void gemm_phase_(const GemmDesc& d, unsigned char* smem, const XMap& xm) {
;     ...
;     const int zc = z, mtc = mt, ntc = nt;
;     __syncthreads();
;     float* rsl = (float*)smem + 13824;
;     if (rpart) {
;       {
;         const float* pp = rpart + (size_t)(mtc * 256 + tid) * 16;
;         float sm = 0.f;
; #pragma unroll
;         for (int q = 0; q < 4; ++q) { const f32x4 v = *(const f32x4*)(pp + q * 4); sm += v[0]; sm += v[1]; sm += v[2]; sm += v[3]; }
;         rsl[tid] = rsqrtf(sm * (1.f / DM) + EPS);
;       }
;       __syncthreads();
.LBB0_617:
	s_setprio 1
	v_lshlrev_b32_e32 v234, 2, v215
	v_add_u32_e32 v234, 0xde20, v234
	ds_read_b128 v[202:205], v234
	ds_read_b128 v[208:211], v234 offset:4096
	ds_read_b128 v[180:183], v234 offset:8192
	ds_read_b128 v[184:187], v234 offset:12288
	ds_read_b128 v[192:195], v234 offset:16384
	s_waitcnt lgkmcnt(0)
	s_and_b64 vcc, exec, s[0:1]
	s_barrier
	s_cbranch_vccz .LBB0_619
	s_waitcnt vmcnt(3)
	v_add_f32_e32 v128, 0, v128
	v_add_f32_e32 v128, v129, v128
	v_add_f32_e32 v128, v130, v128
	v_add_f32_e32 v128, v131, v128
	s_waitcnt vmcnt(2)
	v_add_f32_e32 v128, v132, v128
	v_add_f32_e32 v128, v133, v128
	v_add_f32_e32 v128, v134, v128
	v_add_f32_e32 v128, v135, v128
	s_waitcnt vmcnt(1)
	v_add_f32_e32 v128, v136, v128
	v_add_f32_e32 v128, v137, v128
	v_add_f32_e32 v128, v138, v128
	v_add_f32_e32 v128, v139, v128
	s_waitcnt vmcnt(0)
	v_add_f32_e32 v128, v140, v128
	v_add_f32_e32 v128, v141, v128
	v_add_f32_e32 v128, v142, v128
	v_add_f32_e32 v128, v143, v128
	v_fmamk_f32 v128, v128, 0x3a800000, v193
	v_mul_f32_e32 v129, 0x4b800000, v128
	v_cmp_gt_f32_e32 vcc, s97, v128
	s_nop 1
	v_cndmask_b32_e32 v128, v128, v129, vcc
	v_rsq_f32_e32 v128, v128
	s_nop 0
	v_mul_f32_e32 v129, 0x45800000, v128
	v_cndmask_b32_e32 v128, v128, v129, vcc
	ds_write_b32 v215, v128 offset:55296
	s_waitcnt lgkmcnt(0)
	s_barrier
